# indexer pass-2 loop hand-pipelined (epilogue of stage st-1 beside MFMAs of stage st, packed head sums) on top of combo3
# speedup vs baseline: 1.0376x; 1.0091x over previous
.LBB0_1024:
	ds_read_b128 v[164:167], v99 offset:0
	ds_read_b128 v[168:171], v99 offset:4096
	ds_read_b128 v[172:175], v99 offset:1024
	ds_read_b128 v[176:179], v99 offset:5120
	ds_read_b128 v[230:233], v99 offset:2048
	ds_read_b128 v[234:237], v99 offset:6144
	ds_read_b128 v[238:241], v99 offset:3072
	ds_read_b128 v[242:245], v99 offset:7168
	s_waitcnt lgkmcnt(7)
	v_mfma_f32_32x32x16_bf16 v[16:31], v[34:37], v[164:167], 0
	s_waitcnt lgkmcnt(6)
	v_mfma_f32_32x32x16_bf16 v[0:15], v[34:37], v[168:171], 0
	s_waitcnt vmcnt(3)
	ds_write_b128 v140, v[50:53] offset:8192
	s_add_i32 s4, s18, 5
	s_min_i32 s4, s4, s14
	v_mad_i64_i32 v[164:165], s[4:5], s4, v193, v[116:117]
	global_load_dwordx4 v[50:53], v[164:165], off
	s_waitcnt lgkmcnt(6)
	v_mfma_f32_32x32x16_bf16 v[16:31], v[38:41], v[172:175], v[16:31]
	s_waitcnt lgkmcnt(5)
	v_mfma_f32_32x32x16_bf16 v[0:15], v[38:41], v[176:179], v[0:15]
	s_waitcnt lgkmcnt(4)
	v_mfma_f32_32x32x16_bf16 v[16:31], v[42:45], v[230:233], v[16:31]
	s_waitcnt lgkmcnt(3)
	v_mfma_f32_32x32x16_bf16 v[0:15], v[42:45], v[234:237], v[0:15]
	s_waitcnt lgkmcnt(2)
	v_mfma_f32_32x32x16_bf16 v[16:31], v[46:49], v[238:241], v[16:31]
	s_waitcnt lgkmcnt(1)
	v_mfma_f32_32x32x16_bf16 v[0:15], v[46:49], v[242:245], v[0:15]
	s_waitcnt lgkmcnt(0)
	s_barrier
	s_add_u32 s18, s18, 1
	s_cmp_ge_u32 s18, s13
	s_cbranch_scc1 .Lp2_drain0
.Lp2_c1:
	ds_read_b128 v[164:167], v99 offset:8192
	ds_read_b128 v[168:171], v99 offset:12288
	ds_read_b128 v[172:175], v99 offset:9216
	ds_read_b128 v[176:179], v99 offset:13312
	ds_read_b128 v[230:233], v99 offset:10240
	ds_read_b128 v[234:237], v99 offset:14336
	ds_read_b128 v[238:241], v99 offset:11264
	ds_read_b128 v[242:245], v99 offset:15360
	v_max_i32_e32 v246, 0, v24
	v_max_i32_e32 v247, 0, v16
	v_max_i32_e32 v248, 0, v25
	v_max_i32_e32 v249, 0, v17
	v_max_i32_e32 v154, 0, v26
	v_max_i32_e32 v155, 0, v18
	v_max_i32_e32 v156, 0, v27
	v_max_i32_e32 v157, 0, v19
	s_waitcnt lgkmcnt(7)
	v_mfma_f32_32x32x16_bf16 v[198:213], v[34:37], v[164:167], 0
	v_pk_fma_f32 v[184:185], v[100:101], v[246:247], 0 op_sel_hi:[1,1,0]
	v_pk_fma_f32 v[184:185], v[102:103], v[248:249], v[184:185]
	v_pk_fma_f32 v[184:185], v[104:105], v[154:155], v[184:185]
	v_pk_fma_f32 v[184:185], v[106:107], v[156:157], v[184:185]
	v_max_i32_e32 v246, 0, v28
	v_max_i32_e32 v247, 0, v20
	v_max_i32_e32 v248, 0, v29
	v_max_i32_e32 v249, 0, v21
	s_waitcnt lgkmcnt(6)
	v_mfma_f32_32x32x16_bf16 v[214:229], v[34:37], v[168:171], 0
	s_waitcnt vmcnt(3)
	ds_write_b128 v140, v[54:57]
	s_add_i32 s4, s18, 5
	s_min_i32 s4, s4, s14
	v_mad_i64_i32 v[164:165], s[4:5], s4, v193, v[116:117]
	global_load_dwordx4 v[54:57], v[164:165], off
	v_max_i32_e32 v154, 0, v30
	v_max_i32_e32 v155, 0, v22
	v_max_i32_e32 v156, 0, v31
	v_max_i32_e32 v157, 0, v23
	v_pk_fma_f32 v[184:185], v[108:109], v[246:247], v[184:185]
	v_pk_fma_f32 v[184:185], v[110:111], v[248:249], v[184:185]
	v_pk_fma_f32 v[184:185], v[112:113], v[154:155], v[184:185]
	v_pk_fma_f32 v[184:185], v[114:115], v[156:157], v[184:185]
	s_waitcnt lgkmcnt(6)
	v_mfma_f32_32x32x16_bf16 v[198:213], v[38:41], v[172:175], v[198:213]
	v_bfe_u32 v250, v185, 19, 12
	v_bfe_u32 v197, v184, 19, 12
	v_med3_u32 v250, v250, s94, v194
	v_med3_u32 v197, v197, s94, v194
	v_sub_u32_e32 v246, 0x86f, v250
	v_add_u32_e32 v247, 0xfffffb90, v250
	s_waitcnt lgkmcnt(5)
	v_mfma_f32_32x32x16_bf16 v[214:229], v[38:41], v[176:179], v[214:229]
	v_sub_u32_e32 v248, 0x86f, v197
	v_add_u32_e32 v249, 0xfffffb90, v197
	v_cmp_gt_f32_e32 vcc, 0, v185
	v_cmp_gt_f32_e64 s[52:53], 0, v184
	s_nop 0
	v_cndmask_b32_e32 v250, v247, v246, vcc
	v_cndmask_b32_e64 v197, v249, v248, s[52:53]
	s_waitcnt lgkmcnt(1)
	v_cmp_gt_i32_e32 vcc, v250, v149
	s_and_saveexec_b64 s[4:5], s[50:51]
	s_nop 0
	v_mov_b32_e32 v246, vcc_hi
	v_mov_b32_e32 v247, vcc_lo
	v_cndmask_b32_e64 v246, v246, v247, s[48:49]
	ds_write_b32 v162, v246
	s_or_b64 exec, exec, s[4:5]
	v_cmp_eq_u32_e32 vcc, v250, v149
	s_cbranch_vccz .Lp2_skip1
	s_nop 0
	v_mov_b32_e32 v246, vcc_hi
	v_mov_b32_e32 v247, vcc_lo
	v_cndmask_b32_e64 v246, v246, v247, s[48:49]
	s_and_saveexec_b64 s[4:5], vcc
	s_cbranch_execz .Lp2_join1
	v_and_b32_e32 v247, v246, v127
	v_bcnt_u32_b32 v247, v247, v119
	v_cmp_gt_u32_e32 vcc, s35, v247
	s_and_b64 exec, exec, vcc
	s_cbranch_execz .Lp2_join1
	v_cmp_gt_f32_e64 s[52:53], 0, v185
	v_not_b32_e32 v248, v185
	s_nop 0
	v_cndmask_b32_e64 v33, -|v185|, v248, s[52:53]
	v_lshl_add_u64 v[154:155], v[78:79], 0, s[0:1]
	v_lshl_add_u64 v[154:155], v[154:155], 0, v[32:33]
	v_lshl_add_u32 v248, v247, 3, v160
	ds_write_b64 v248, v[154:155] offset:2048
.Lp2_join1:
	s_or_b64 exec, exec, s[4:5]
	v_bcnt_u32_b32 v119, v246, v119
.Lp2_skip1:
	v_mfma_f32_32x32x16_bf16 v[198:213], v[42:45], v[230:233], v[198:213]
	v_cmp_gt_i32_e32 vcc, v197, v159
	s_and_saveexec_b64 s[4:5], s[50:51]
	s_nop 0
	v_mov_b32_e32 v246, vcc_hi
	v_mov_b32_e32 v247, vcc_lo
	v_cndmask_b32_e64 v246, v246, v247, s[48:49]
	ds_write_b32 v162, v246 offset:1024
	s_or_b64 exec, exec, s[4:5]
	v_cmp_eq_u32_e32 vcc, v197, v159
	s_cbranch_vccz .Lp2_skip2
	s_nop 0
	v_mov_b32_e32 v246, vcc_hi
	v_mov_b32_e32 v247, vcc_lo
	v_cndmask_b32_e64 v246, v246, v247, s[48:49]
	s_and_saveexec_b64 s[4:5], vcc
	s_cbranch_execz .Lp2_join2
	v_and_b32_e32 v247, v246, v127
	v_bcnt_u32_b32 v247, v247, v118
	v_cmp_gt_u32_e32 vcc, s35, v247
	s_and_b64 exec, exec, vcc
	s_cbranch_execz .Lp2_join2
	v_cmp_gt_f32_e64 s[52:53], 0, v184
	v_not_b32_e32 v248, v184
	s_nop 0
	v_cndmask_b32_e64 v33, -|v184|, v248, s[52:53]
	v_lshl_add_u64 v[154:155], v[78:79], 0, s[0:1]
	v_lshl_add_u64 v[154:155], v[154:155], 0, v[32:33]
	v_lshl_add_u32 v248, v247, 3, v161
	ds_write_b64 v248, v[154:155] offset:2048
.Lp2_join2:
	s_or_b64 exec, exec, s[4:5]
	v_bcnt_u32_b32 v118, v246, v118
.Lp2_skip2:
	v_mfma_f32_32x32x16_bf16 v[214:229], v[42:45], v[234:237], v[214:229]
	v_max_i32_e32 v246, 0, v8
	v_max_i32_e32 v247, 0, v0
	v_max_i32_e32 v248, 0, v9
	v_max_i32_e32 v249, 0, v1
	v_max_i32_e32 v154, 0, v10
	v_max_i32_e32 v155, 0, v2
	v_max_i32_e32 v156, 0, v11
	v_max_i32_e32 v157, 0, v3
	v_mfma_f32_32x32x16_bf16 v[198:213], v[46:49], v[238:241], v[198:213]
	v_pk_fma_f32 v[184:185], v[100:101], v[246:247], 0 op_sel_hi:[1,1,0]
	v_pk_fma_f32 v[184:185], v[102:103], v[248:249], v[184:185]
	v_pk_fma_f32 v[184:185], v[104:105], v[154:155], v[184:185]
	v_pk_fma_f32 v[184:185], v[106:107], v[156:157], v[184:185]
	v_max_i32_e32 v246, 0, v12
	v_max_i32_e32 v247, 0, v4
	v_max_i32_e32 v248, 0, v13
	v_max_i32_e32 v249, 0, v5
	v_mfma_f32_32x32x16_bf16 v[214:229], v[46:49], v[242:245], v[214:229]
	v_max_i32_e32 v154, 0, v14
	v_max_i32_e32 v155, 0, v6
	v_max_i32_e32 v156, 0, v15
	v_max_i32_e32 v157, 0, v7
	v_pk_fma_f32 v[184:185], v[108:109], v[246:247], v[184:185]
	v_pk_fma_f32 v[184:185], v[110:111], v[248:249], v[184:185]
	v_pk_fma_f32 v[184:185], v[112:113], v[154:155], v[184:185]
	v_pk_fma_f32 v[184:185], v[114:115], v[156:157], v[184:185]
	v_bfe_u32 v250, v185, 19, 12
	v_bfe_u32 v197, v184, 19, 12
	v_med3_u32 v250, v250, s94, v194
	v_med3_u32 v197, v197, s94, v194
	v_sub_u32_e32 v246, 0x86f, v250
	v_add_u32_e32 v247, 0xfffffb90, v250
	v_sub_u32_e32 v248, 0x86f, v197
	v_add_u32_e32 v249, 0xfffffb90, v197
	v_cmp_gt_f32_e32 vcc, 0, v185
	v_cmp_gt_f32_e64 s[52:53], 0, v184
	s_nop 0
	v_cndmask_b32_e32 v250, v247, v246, vcc
	v_cndmask_b32_e64 v197, v249, v248, s[52:53]
	v_cmp_gt_i32_e32 vcc, v250, v149
	s_and_saveexec_b64 s[4:5], s[50:51]
	s_nop 0
	v_mov_b32_e32 v246, vcc_hi
	v_mov_b32_e32 v247, vcc_lo
	v_cndmask_b32_e64 v246, v246, v247, s[48:49]
	ds_write_b32 v162, v246 offset:4
	s_or_b64 exec, exec, s[4:5]
	v_cmp_eq_u32_e32 vcc, v250, v149
	s_cbranch_vccz .Lp2_skip3
	s_nop 0
	v_mov_b32_e32 v246, vcc_hi
	v_mov_b32_e32 v247, vcc_lo
	v_cndmask_b32_e64 v246, v246, v247, s[48:49]
	s_and_saveexec_b64 s[4:5], vcc
	s_cbranch_execz .Lp2_join3
	v_and_b32_e32 v247, v246, v127
	v_bcnt_u32_b32 v247, v247, v119
	v_cmp_gt_u32_e32 vcc, s35, v247
	s_and_b64 exec, exec, vcc
	s_cbranch_execz .Lp2_join3
	v_cmp_gt_f32_e64 s[52:53], 0, v185
	v_not_b32_e32 v248, v185
	s_nop 0
	v_cndmask_b32_e64 v33, -|v185|, v248, s[52:53]
	v_lshl_add_u64 v[154:155], v[96:97], 0, s[0:1]
	v_lshl_add_u64 v[154:155], v[154:155], 0, v[32:33]
	v_lshl_add_u32 v248, v247, 3, v160
	ds_write_b64 v248, v[154:155] offset:2048

.Lp2_skip3:
	v_cmp_gt_i32_e32 vcc, v197, v159
	s_and_saveexec_b64 s[4:5], s[50:51]
	s_nop 0
	v_mov_b32_e32 v246, vcc_hi
	v_mov_b32_e32 v247, vcc_lo
	v_cndmask_b32_e64 v246, v246, v247, s[48:49]
	ds_write_b32 v162, v246 offset:1028
	s_or_b64 exec, exec, s[4:5]
	v_cmp_eq_u32_e32 vcc, v197, v159
	s_cbranch_vccz .Lp2_skip4
	s_nop 0
	v_mov_b32_e32 v246, vcc_hi
	v_mov_b32_e32 v247, vcc_lo
	v_cndmask_b32_e64 v246, v246, v247, s[48:49]
	s_and_saveexec_b64 s[4:5], vcc
	s_cbranch_execz .Lp2_join4
	v_and_b32_e32 v247, v246, v127
	v_bcnt_u32_b32 v247, v247, v118
	v_cmp_gt_u32_e32 vcc, s35, v247
	s_and_b64 exec, exec, vcc
	s_cbranch_execz .Lp2_join4
	v_cmp_gt_f32_e64 s[52:53], 0, v184
	v_not_b32_e32 v248, v184
	s_nop 0
	v_cndmask_b32_e64 v33, -|v184|, v248, s[52:53]
	v_lshl_add_u64 v[154:155], v[96:97], 0, s[0:1]
	v_lshl_add_u64 v[154:155], v[154:155], 0, v[32:33]
	v_lshl_add_u32 v248, v247, 3, v161
	ds_write_b64 v248, v[154:155] offset:2048

.Lp2_skip4:
	s_waitcnt lgkmcnt(0)
	s_barrier
	s_add_u32 s18, s18, 1
	s_cmp_ge_u32 s18, s13
	s_cbranch_scc1 .Lp2_drain1
.Lp2_c2:
	ds_read_b128 v[164:167], v99 offset:0
	ds_read_b128 v[168:171], v99 offset:4096
	ds_read_b128 v[172:175], v99 offset:1024
	ds_read_b128 v[176:179], v99 offset:5120
	ds_read_b128 v[230:233], v99 offset:2048
	ds_read_b128 v[234:237], v99 offset:6144
	ds_read_b128 v[238:241], v99 offset:3072
	ds_read_b128 v[242:245], v99 offset:7168
	v_max_i32_e32 v246, 0, v206
	v_max_i32_e32 v247, 0, v198
	v_max_i32_e32 v248, 0, v207
	v_max_i32_e32 v249, 0, v199
	v_max_i32_e32 v154, 0, v208
	v_max_i32_e32 v155, 0, v200
	v_max_i32_e32 v156, 0, v209
	v_max_i32_e32 v157, 0, v201
	s_waitcnt lgkmcnt(7)
	v_mfma_f32_32x32x16_bf16 v[16:31], v[34:37], v[164:167], 0
	v_pk_fma_f32 v[184:185], v[100:101], v[246:247], 0 op_sel_hi:[1,1,0]
	v_pk_fma_f32 v[184:185], v[102:103], v[248:249], v[184:185]
	v_pk_fma_f32 v[184:185], v[104:105], v[154:155], v[184:185]
	v_pk_fma_f32 v[184:185], v[106:107], v[156:157], v[184:185]
	v_max_i32_e32 v246, 0, v210
	v_max_i32_e32 v247, 0, v202
	v_max_i32_e32 v248, 0, v211
	v_max_i32_e32 v249, 0, v203
	s_waitcnt lgkmcnt(6)
	v_mfma_f32_32x32x16_bf16 v[0:15], v[34:37], v[168:171], 0
	s_waitcnt vmcnt(3)
	ds_write_b128 v140, v[58:61] offset:8192
	s_add_i32 s4, s18, 5
	s_min_i32 s4, s4, s14
	v_mad_i64_i32 v[164:165], s[4:5], s4, v193, v[116:117]
	global_load_dwordx4 v[58:61], v[164:165], off
	v_max_i32_e32 v154, 0, v212
	v_max_i32_e32 v155, 0, v204
	v_max_i32_e32 v156, 0, v213
	v_max_i32_e32 v157, 0, v205
	v_pk_fma_f32 v[184:185], v[108:109], v[246:247], v[184:185]
	v_pk_fma_f32 v[184:185], v[110:111], v[248:249], v[184:185]
	v_pk_fma_f32 v[184:185], v[112:113], v[154:155], v[184:185]
	v_pk_fma_f32 v[184:185], v[114:115], v[156:157], v[184:185]
	s_waitcnt lgkmcnt(6)
	v_mfma_f32_32x32x16_bf16 v[16:31], v[38:41], v[172:175], v[16:31]
	v_bfe_u32 v250, v185, 19, 12
	v_bfe_u32 v197, v184, 19, 12
	v_med3_u32 v250, v250, s94, v194
	v_med3_u32 v197, v197, s94, v194
	v_sub_u32_e32 v246, 0x86f, v250
	v_add_u32_e32 v247, 0xfffffb90, v250
	s_waitcnt lgkmcnt(5)
	v_mfma_f32_32x32x16_bf16 v[0:15], v[38:41], v[176:179], v[0:15]
	v_sub_u32_e32 v248, 0x86f, v197
	v_add_u32_e32 v249, 0xfffffb90, v197
	v_cmp_gt_f32_e32 vcc, 0, v185
	v_cmp_gt_f32_e64 s[52:53], 0, v184
	s_nop 0
	v_cndmask_b32_e32 v250, v247, v246, vcc
	v_cndmask_b32_e64 v197, v249, v248, s[52:53]
	s_waitcnt lgkmcnt(1)
	v_cmp_gt_i32_e32 vcc, v250, v149
	s_and_saveexec_b64 s[4:5], s[50:51]
	s_nop 0
	v_mov_b32_e32 v246, vcc_hi
	v_mov_b32_e32 v247, vcc_lo
	v_cndmask_b32_e64 v246, v246, v247, s[48:49]
	ds_write_b32 v162, v246 offset:8
	s_or_b64 exec, exec, s[4:5]
	v_cmp_eq_u32_e32 vcc, v250, v149
	s_cbranch_vccz .Lp2_skip5
	s_nop 0
	v_mov_b32_e32 v246, vcc_hi
	v_mov_b32_e32 v247, vcc_lo
	v_cndmask_b32_e64 v246, v246, v247, s[48:49]
	s_and_saveexec_b64 s[4:5], vcc
	s_cbranch_execz .Lp2_join5
	v_and_b32_e32 v247, v246, v127
	v_bcnt_u32_b32 v247, v247, v119
	v_cmp_gt_u32_e32 vcc, s35, v247
	s_and_b64 exec, exec, vcc
	s_cbranch_execz .Lp2_join5
	v_cmp_gt_f32_e64 s[52:53], 0, v185
	v_not_b32_e32 v248, v185
	s_nop 0
	v_cndmask_b32_e64 v33, -|v185|, v248, s[52:53]
	v_lshl_add_u64 v[154:155], v[92:93], 0, s[0:1]
	v_lshl_add_u64 v[154:155], v[154:155], 0, v[32:33]
	v_lshl_add_u32 v248, v247, 3, v160
	ds_write_b64 v248, v[154:155] offset:2048

.Lp2_skip5:
	v_mfma_f32_32x32x16_bf16 v[16:31], v[42:45], v[230:233], v[16:31]
	v_cmp_gt_i32_e32 vcc, v197, v159
	s_and_saveexec_b64 s[4:5], s[50:51]
	s_nop 0
	v_mov_b32_e32 v246, vcc_hi
	v_mov_b32_e32 v247, vcc_lo
	v_cndmask_b32_e64 v246, v246, v247, s[48:49]
	ds_write_b32 v162, v246 offset:1032
	s_or_b64 exec, exec, s[4:5]
	v_cmp_eq_u32_e32 vcc, v197, v159
	s_cbranch_vccz .Lp2_skip6
	s_nop 0
	v_mov_b32_e32 v246, vcc_hi
	v_mov_b32_e32 v247, vcc_lo
	v_cndmask_b32_e64 v246, v246, v247, s[48:49]
	s_and_saveexec_b64 s[4:5], vcc
	s_cbranch_execz .Lp2_join6
	v_and_b32_e32 v247, v246, v127
	v_bcnt_u32_b32 v247, v247, v118
	v_cmp_gt_u32_e32 vcc, s35, v247
	s_and_b64 exec, exec, vcc
	s_cbranch_execz .Lp2_join6
	v_cmp_gt_f32_e64 s[52:53], 0, v184
	v_not_b32_e32 v248, v184
	s_nop 0
	v_cndmask_b32_e64 v33, -|v184|, v248, s[52:53]
	v_lshl_add_u64 v[154:155], v[92:93], 0, s[0:1]
	v_lshl_add_u64 v[154:155], v[154:155], 0, v[32:33]
	v_lshl_add_u32 v248, v247, 3, v161
	ds_write_b64 v248, v[154:155] offset:2048

.Lp2_skip6:
	v_mfma_f32_32x32x16_bf16 v[0:15], v[42:45], v[234:237], v[0:15]
	v_max_i32_e32 v246, 0, v222
	v_max_i32_e32 v247, 0, v214
	v_max_i32_e32 v248, 0, v223
	v_max_i32_e32 v249, 0, v215
	v_max_i32_e32 v154, 0, v224
	v_max_i32_e32 v155, 0, v216
	v_max_i32_e32 v156, 0, v225
	v_max_i32_e32 v157, 0, v217
	v_mfma_f32_32x32x16_bf16 v[16:31], v[46:49], v[238:241], v[16:31]
	v_pk_fma_f32 v[184:185], v[100:101], v[246:247], 0 op_sel_hi:[1,1,0]
	v_pk_fma_f32 v[184:185], v[102:103], v[248:249], v[184:185]
	v_pk_fma_f32 v[184:185], v[104:105], v[154:155], v[184:185]
	v_pk_fma_f32 v[184:185], v[106:107], v[156:157], v[184:185]
	v_max_i32_e32 v246, 0, v226
	v_max_i32_e32 v247, 0, v218
	v_max_i32_e32 v248, 0, v227
	v_max_i32_e32 v249, 0, v219
	v_mfma_f32_32x32x16_bf16 v[0:15], v[46:49], v[242:245], v[0:15]
	v_max_i32_e32 v154, 0, v228
	v_max_i32_e32 v155, 0, v220
	v_max_i32_e32 v156, 0, v229
	v_max_i32_e32 v157, 0, v221
	v_pk_fma_f32 v[184:185], v[108:109], v[246:247], v[184:185]
	v_pk_fma_f32 v[184:185], v[110:111], v[248:249], v[184:185]
	v_pk_fma_f32 v[184:185], v[112:113], v[154:155], v[184:185]
	v_pk_fma_f32 v[184:185], v[114:115], v[156:157], v[184:185]
	v_bfe_u32 v250, v185, 19, 12
	v_bfe_u32 v197, v184, 19, 12
	v_med3_u32 v250, v250, s94, v194
	v_med3_u32 v197, v197, s94, v194
	v_sub_u32_e32 v246, 0x86f, v250
	v_add_u32_e32 v247, 0xfffffb90, v250
	v_sub_u32_e32 v248, 0x86f, v197
	v_add_u32_e32 v249, 0xfffffb90, v197
	v_cmp_gt_f32_e32 vcc, 0, v185
	v_cmp_gt_f32_e64 s[52:53], 0, v184
	s_nop 0
	v_cndmask_b32_e32 v250, v247, v246, vcc
	v_cndmask_b32_e64 v197, v249, v248, s[52:53]
	v_cmp_gt_i32_e32 vcc, v250, v149
	s_and_saveexec_b64 s[4:5], s[50:51]
	s_nop 0
	v_mov_b32_e32 v246, vcc_hi
	v_mov_b32_e32 v247, vcc_lo
	v_cndmask_b32_e64 v246, v246, v247, s[48:49]
	ds_write_b32 v162, v246 offset:12
	s_or_b64 exec, exec, s[4:5]
	v_cmp_eq_u32_e32 vcc, v250, v149
	s_cbranch_vccz .Lp2_skip7
	s_nop 0
	v_mov_b32_e32 v246, vcc_hi
	v_mov_b32_e32 v247, vcc_lo
	v_cndmask_b32_e64 v246, v246, v247, s[48:49]
	s_and_saveexec_b64 s[4:5], vcc
	s_cbranch_execz .Lp2_join7
	v_and_b32_e32 v247, v246, v127
	v_bcnt_u32_b32 v247, v247, v119
	v_cmp_gt_u32_e32 vcc, s35, v247
	s_and_b64 exec, exec, vcc
	s_cbranch_execz .Lp2_join7
	v_cmp_gt_f32_e64 s[52:53], 0, v185
	v_not_b32_e32 v248, v185
	s_nop 0
	v_cndmask_b32_e64 v33, -|v185|, v248, s[52:53]
	v_lshl_add_u64 v[154:155], v[94:95], 0, s[0:1]
	v_lshl_add_u64 v[154:155], v[154:155], 0, v[32:33]
	v_lshl_add_u32 v248, v247, 3, v160
	ds_write_b64 v248, v[154:155] offset:2048

.Lp2_skip7:
	v_cmp_gt_i32_e32 vcc, v197, v159
	s_and_saveexec_b64 s[4:5], s[50:51]
	s_nop 0
	v_mov_b32_e32 v246, vcc_hi
	v_mov_b32_e32 v247, vcc_lo
	v_cndmask_b32_e64 v246, v246, v247, s[48:49]
	ds_write_b32 v162, v246 offset:1036
	s_or_b64 exec, exec, s[4:5]
	v_cmp_eq_u32_e32 vcc, v197, v159
	s_cbranch_vccz .Lp2_skip8
	s_nop 0
	v_mov_b32_e32 v246, vcc_hi
	v_mov_b32_e32 v247, vcc_lo
	v_cndmask_b32_e64 v246, v246, v247, s[48:49]
	s_and_saveexec_b64 s[4:5], vcc
	s_cbranch_execz .Lp2_join8
	v_and_b32_e32 v247, v246, v127
	v_bcnt_u32_b32 v247, v247, v118
	v_cmp_gt_u32_e32 vcc, s35, v247
	s_and_b64 exec, exec, vcc
	s_cbranch_execz .Lp2_join8
	v_cmp_gt_f32_e64 s[52:53], 0, v184
	v_not_b32_e32 v248, v184
	s_nop 0
	v_cndmask_b32_e64 v33, -|v184|, v248, s[52:53]
	v_lshl_add_u64 v[154:155], v[94:95], 0, s[0:1]
	v_lshl_add_u64 v[154:155], v[154:155], 0, v[32:33]
	v_lshl_add_u32 v248, v247, 3, v161
	ds_write_b64 v248, v[154:155] offset:2048

.Lp2_c3:
	ds_read_b128 v[164:167], v99 offset:8192
	ds_read_b128 v[168:171], v99 offset:12288
	ds_read_b128 v[172:175], v99 offset:9216
	ds_read_b128 v[176:179], v99 offset:13312
	ds_read_b128 v[230:233], v99 offset:10240
	ds_read_b128 v[234:237], v99 offset:14336
	ds_read_b128 v[238:241], v99 offset:11264
	ds_read_b128 v[242:245], v99 offset:15360
	v_max_i32_e32 v246, 0, v24
	v_max_i32_e32 v247, 0, v16
	v_max_i32_e32 v248, 0, v25
	v_max_i32_e32 v249, 0, v17
	v_max_i32_e32 v154, 0, v26
	v_max_i32_e32 v155, 0, v18
	v_max_i32_e32 v156, 0, v27
	v_max_i32_e32 v157, 0, v19
	s_waitcnt lgkmcnt(7)
	v_mfma_f32_32x32x16_bf16 v[198:213], v[34:37], v[164:167], 0
	v_pk_fma_f32 v[184:185], v[100:101], v[246:247], 0 op_sel_hi:[1,1,0]
	v_pk_fma_f32 v[184:185], v[102:103], v[248:249], v[184:185]
	v_pk_fma_f32 v[184:185], v[104:105], v[154:155], v[184:185]
	v_pk_fma_f32 v[184:185], v[106:107], v[156:157], v[184:185]
	v_max_i32_e32 v246, 0, v28
	v_max_i32_e32 v247, 0, v20
	v_max_i32_e32 v248, 0, v29
	v_max_i32_e32 v249, 0, v21
	s_waitcnt lgkmcnt(6)
	v_mfma_f32_32x32x16_bf16 v[214:229], v[34:37], v[168:171], 0
	s_waitcnt vmcnt(3)
	ds_write_b128 v140, v[62:65]
	s_add_i32 s4, s18, 5
	s_min_i32 s4, s4, s14
	v_mad_i64_i32 v[164:165], s[4:5], s4, v193, v[116:117]
	global_load_dwordx4 v[62:65], v[164:165], off
	v_max_i32_e32 v154, 0, v30
	v_max_i32_e32 v155, 0, v22
	v_max_i32_e32 v156, 0, v31
	v_max_i32_e32 v157, 0, v23
	v_pk_fma_f32 v[184:185], v[108:109], v[246:247], v[184:185]
	v_pk_fma_f32 v[184:185], v[110:111], v[248:249], v[184:185]
	v_pk_fma_f32 v[184:185], v[112:113], v[154:155], v[184:185]
	v_pk_fma_f32 v[184:185], v[114:115], v[156:157], v[184:185]
	s_waitcnt lgkmcnt(6)
	v_mfma_f32_32x32x16_bf16 v[198:213], v[38:41], v[172:175], v[198:213]
	v_bfe_u32 v250, v185, 19, 12
	v_bfe_u32 v197, v184, 19, 12
	v_med3_u32 v250, v250, s94, v194
	v_med3_u32 v197, v197, s94, v194
	v_sub_u32_e32 v246, 0x86f, v250
	v_add_u32_e32 v247, 0xfffffb90, v250
	s_waitcnt lgkmcnt(5)
	v_mfma_f32_32x32x16_bf16 v[214:229], v[38:41], v[176:179], v[214:229]
	v_sub_u32_e32 v248, 0x86f, v197
	v_add_u32_e32 v249, 0xfffffb90, v197
	v_cmp_gt_f32_e32 vcc, 0, v185
	v_cmp_gt_f32_e64 s[52:53], 0, v184
	s_nop 0
	v_cndmask_b32_e32 v250, v247, v246, vcc
	v_cndmask_b32_e64 v197, v249, v248, s[52:53]
	s_waitcnt lgkmcnt(1)
	v_cmp_gt_i32_e32 vcc, v250, v149
	s_and_saveexec_b64 s[4:5], s[50:51]
	s_nop 0
	v_mov_b32_e32 v246, vcc_hi
	v_mov_b32_e32 v247, vcc_lo
	v_cndmask_b32_e64 v246, v246, v247, s[48:49]
	ds_write_b32 v162, v246 offset:16
	s_or_b64 exec, exec, s[4:5]
	v_cmp_eq_u32_e32 vcc, v250, v149
	s_cbranch_vccz .Lp2_skip9
	s_nop 0
	v_mov_b32_e32 v246, vcc_hi
	v_mov_b32_e32 v247, vcc_lo
	v_cndmask_b32_e64 v246, v246, v247, s[48:49]
	s_and_saveexec_b64 s[4:5], vcc
	s_cbranch_execz .Lp2_join9
	v_and_b32_e32 v247, v246, v127
	v_bcnt_u32_b32 v247, v247, v119
	v_cmp_gt_u32_e32 vcc, s35, v247
	s_and_b64 exec, exec, vcc
	s_cbranch_execz .Lp2_join9
	v_cmp_gt_f32_e64 s[52:53], 0, v185
	v_not_b32_e32 v248, v185
	s_nop 0
	v_cndmask_b32_e64 v33, -|v185|, v248, s[52:53]
	v_lshl_add_u64 v[154:155], v[90:91], 0, s[0:1]
	v_lshl_add_u64 v[154:155], v[154:155], 0, v[32:33]
	v_lshl_add_u32 v248, v247, 3, v160
	ds_write_b64 v248, v[154:155] offset:2048

.Lp2_skip9:
	v_mfma_f32_32x32x16_bf16 v[198:213], v[42:45], v[230:233], v[198:213]
	v_cmp_gt_i32_e32 vcc, v197, v159
	s_and_saveexec_b64 s[4:5], s[50:51]
	s_nop 0
	v_mov_b32_e32 v246, vcc_hi
	v_mov_b32_e32 v247, vcc_lo
	v_cndmask_b32_e64 v246, v246, v247, s[48:49]
	ds_write_b32 v162, v246 offset:1040
	s_or_b64 exec, exec, s[4:5]
	v_cmp_eq_u32_e32 vcc, v197, v159
	s_cbranch_vccz .Lp2_skip10
	s_nop 0
	v_mov_b32_e32 v246, vcc_hi
	v_mov_b32_e32 v247, vcc_lo
	v_cndmask_b32_e64 v246, v246, v247, s[48:49]
	s_and_saveexec_b64 s[4:5], vcc
	s_cbranch_execz .Lp2_join10
	v_and_b32_e32 v247, v246, v127
	v_bcnt_u32_b32 v247, v247, v118
	v_cmp_gt_u32_e32 vcc, s35, v247
	s_and_b64 exec, exec, vcc
	s_cbranch_execz .Lp2_join10
	v_cmp_gt_f32_e64 s[52:53], 0, v184
	v_not_b32_e32 v248, v184
	s_nop 0
	v_cndmask_b32_e64 v33, -|v184|, v248, s[52:53]
	v_lshl_add_u64 v[154:155], v[90:91], 0, s[0:1]
	v_lshl_add_u64 v[154:155], v[154:155], 0, v[32:33]
	v_lshl_add_u32 v248, v247, 3, v161
	ds_write_b64 v248, v[154:155] offset:2048

.Lp2_skip10:
	v_mfma_f32_32x32x16_bf16 v[214:229], v[42:45], v[234:237], v[214:229]
	v_max_i32_e32 v246, 0, v8
	v_max_i32_e32 v247, 0, v0
	v_max_i32_e32 v248, 0, v9
	v_max_i32_e32 v249, 0, v1
	v_max_i32_e32 v154, 0, v10
	v_max_i32_e32 v155, 0, v2
	v_max_i32_e32 v156, 0, v11
	v_max_i32_e32 v157, 0, v3
	v_mfma_f32_32x32x16_bf16 v[198:213], v[46:49], v[238:241], v[198:213]
	v_pk_fma_f32 v[184:185], v[100:101], v[246:247], 0 op_sel_hi:[1,1,0]
	v_pk_fma_f32 v[184:185], v[102:103], v[248:249], v[184:185]
	v_pk_fma_f32 v[184:185], v[104:105], v[154:155], v[184:185]
	v_pk_fma_f32 v[184:185], v[106:107], v[156:157], v[184:185]
	v_max_i32_e32 v246, 0, v12
	v_max_i32_e32 v247, 0, v4
	v_max_i32_e32 v248, 0, v13
	v_max_i32_e32 v249, 0, v5
	v_mfma_f32_32x32x16_bf16 v[214:229], v[46:49], v[242:245], v[214:229]
	v_max_i32_e32 v154, 0, v14
	v_max_i32_e32 v155, 0, v6
	v_max_i32_e32 v156, 0, v15
	v_max_i32_e32 v157, 0, v7
	v_pk_fma_f32 v[184:185], v[108:109], v[246:247], v[184:185]
	v_pk_fma_f32 v[184:185], v[110:111], v[248:249], v[184:185]
	v_pk_fma_f32 v[184:185], v[112:113], v[154:155], v[184:185]
	v_pk_fma_f32 v[184:185], v[114:115], v[156:157], v[184:185]
	v_bfe_u32 v250, v185, 19, 12
	v_bfe_u32 v197, v184, 19, 12
	v_med3_u32 v250, v250, s94, v194
	v_med3_u32 v197, v197, s94, v194
	v_sub_u32_e32 v246, 0x86f, v250
	v_add_u32_e32 v247, 0xfffffb90, v250
	v_sub_u32_e32 v248, 0x86f, v197
	v_add_u32_e32 v249, 0xfffffb90, v197
	v_cmp_gt_f32_e32 vcc, 0, v185
	v_cmp_gt_f32_e64 s[52:53], 0, v184
	s_nop 0
	v_cndmask_b32_e32 v250, v247, v246, vcc
	v_cndmask_b32_e64 v197, v249, v248, s[52:53]
	v_cmp_gt_i32_e32 vcc, v250, v149
	s_and_saveexec_b64 s[4:5], s[50:51]
	s_nop 0
	v_mov_b32_e32 v246, vcc_hi
	v_mov_b32_e32 v247, vcc_lo
	v_cndmask_b32_e64 v246, v246, v247, s[48:49]
	ds_write_b32 v162, v246 offset:20
	s_or_b64 exec, exec, s[4:5]
	v_cmp_eq_u32_e32 vcc, v250, v149
	s_cbranch_vccz .Lp2_skip11
	s_nop 0
	v_mov_b32_e32 v246, vcc_hi
	v_mov_b32_e32 v247, vcc_lo
	v_cndmask_b32_e64 v246, v246, v247, s[48:49]
	s_and_saveexec_b64 s[4:5], vcc
	s_cbranch_execz .Lp2_join11
	v_and_b32_e32 v247, v246, v127
	v_bcnt_u32_b32 v247, v247, v119
	v_cmp_gt_u32_e32 vcc, s35, v247
	s_and_b64 exec, exec, vcc
	s_cbranch_execz .Lp2_join11
	v_cmp_gt_f32_e64 s[52:53], 0, v185
	v_not_b32_e32 v248, v185
	s_nop 0
	v_cndmask_b32_e64 v33, -|v185|, v248, s[52:53]
	v_lshl_add_u64 v[154:155], v[88:89], 0, s[0:1]
	v_lshl_add_u64 v[154:155], v[154:155], 0, v[32:33]
	v_lshl_add_u32 v248, v247, 3, v160
	ds_write_b64 v248, v[154:155] offset:2048

.Lp2_skip11:
	v_cmp_gt_i32_e32 vcc, v197, v159
	s_and_saveexec_b64 s[4:5], s[50:51]
	s_nop 0
	v_mov_b32_e32 v246, vcc_hi
	v_mov_b32_e32 v247, vcc_lo
	v_cndmask_b32_e64 v246, v246, v247, s[48:49]
	ds_write_b32 v162, v246 offset:1044
	s_or_b64 exec, exec, s[4:5]
	v_cmp_eq_u32_e32 vcc, v197, v159
	s_cbranch_vccz .Lp2_skip12
	s_nop 0
	v_mov_b32_e32 v246, vcc_hi
	v_mov_b32_e32 v247, vcc_lo
	v_cndmask_b32_e64 v246, v246, v247, s[48:49]
	s_and_saveexec_b64 s[4:5], vcc
	s_cbranch_execz .Lp2_join12
	v_and_b32_e32 v247, v246, v127
	v_bcnt_u32_b32 v247, v247, v118
	v_cmp_gt_u32_e32 vcc, s35, v247
	s_and_b64 exec, exec, vcc
	s_cbranch_execz .Lp2_join12
	v_cmp_gt_f32_e64 s[52:53], 0, v184
	v_not_b32_e32 v248, v184
	s_nop 0
	v_cndmask_b32_e64 v33, -|v184|, v248, s[52:53]
	v_lshl_add_u64 v[154:155], v[88:89], 0, s[0:1]
	v_lshl_add_u64 v[154:155], v[154:155], 0, v[32:33]
	v_lshl_add_u32 v248, v247, 3, v161
	ds_write_b64 v248, v[154:155] offset:2048

.Lp2_c0:
	ds_read_b128 v[164:167], v99 offset:0
	ds_read_b128 v[168:171], v99 offset:4096
	ds_read_b128 v[172:175], v99 offset:1024
	ds_read_b128 v[176:179], v99 offset:5120
	ds_read_b128 v[230:233], v99 offset:2048
	ds_read_b128 v[234:237], v99 offset:6144
	ds_read_b128 v[238:241], v99 offset:3072
	ds_read_b128 v[242:245], v99 offset:7168
	v_max_i32_e32 v246, 0, v206
	v_max_i32_e32 v247, 0, v198
	v_max_i32_e32 v248, 0, v207
	v_max_i32_e32 v249, 0, v199
	v_max_i32_e32 v154, 0, v208
	v_max_i32_e32 v155, 0, v200
	v_max_i32_e32 v156, 0, v209
	v_max_i32_e32 v157, 0, v201
	s_waitcnt lgkmcnt(7)
	v_mfma_f32_32x32x16_bf16 v[16:31], v[34:37], v[164:167], 0
	v_pk_fma_f32 v[184:185], v[100:101], v[246:247], 0 op_sel_hi:[1,1,0]
	v_pk_fma_f32 v[184:185], v[102:103], v[248:249], v[184:185]
	v_pk_fma_f32 v[184:185], v[104:105], v[154:155], v[184:185]
	v_pk_fma_f32 v[184:185], v[106:107], v[156:157], v[184:185]
	v_max_i32_e32 v246, 0, v210
	v_max_i32_e32 v247, 0, v202
	v_max_i32_e32 v248, 0, v211
	v_max_i32_e32 v249, 0, v203
	s_waitcnt lgkmcnt(6)
	v_mfma_f32_32x32x16_bf16 v[0:15], v[34:37], v[168:171], 0
	s_waitcnt vmcnt(3)
	ds_write_b128 v140, v[50:53] offset:8192
	s_add_i32 s4, s18, 5
	s_min_i32 s4, s4, s14
	v_mad_i64_i32 v[164:165], s[4:5], s4, v193, v[116:117]
	global_load_dwordx4 v[50:53], v[164:165], off
	v_max_i32_e32 v154, 0, v212
	v_max_i32_e32 v155, 0, v204
	v_max_i32_e32 v156, 0, v213
	v_max_i32_e32 v157, 0, v205
	v_pk_fma_f32 v[184:185], v[108:109], v[246:247], v[184:185]
	v_pk_fma_f32 v[184:185], v[110:111], v[248:249], v[184:185]
	v_pk_fma_f32 v[184:185], v[112:113], v[154:155], v[184:185]
	v_pk_fma_f32 v[184:185], v[114:115], v[156:157], v[184:185]
	s_waitcnt lgkmcnt(6)
	v_mfma_f32_32x32x16_bf16 v[16:31], v[38:41], v[172:175], v[16:31]
	v_bfe_u32 v250, v185, 19, 12
	v_bfe_u32 v197, v184, 19, 12
	v_med3_u32 v250, v250, s94, v194
	v_med3_u32 v197, v197, s94, v194
	v_sub_u32_e32 v246, 0x86f, v250
	v_add_u32_e32 v247, 0xfffffb90, v250
	s_waitcnt lgkmcnt(5)
	v_mfma_f32_32x32x16_bf16 v[0:15], v[38:41], v[176:179], v[0:15]
	v_sub_u32_e32 v248, 0x86f, v197
	v_add_u32_e32 v249, 0xfffffb90, v197
	v_cmp_gt_f32_e32 vcc, 0, v185
	v_cmp_gt_f32_e64 s[52:53], 0, v184
	s_nop 0
	v_cndmask_b32_e32 v250, v247, v246, vcc
	v_cndmask_b32_e64 v197, v249, v248, s[52:53]
	s_waitcnt lgkmcnt(1)
	v_cmp_gt_i32_e32 vcc, v250, v149
	s_and_saveexec_b64 s[4:5], s[50:51]
	s_nop 0
	v_mov_b32_e32 v246, vcc_hi
	v_mov_b32_e32 v247, vcc_lo
	v_cndmask_b32_e64 v246, v246, v247, s[48:49]
	ds_write_b32 v162, v246 offset:24
	s_or_b64 exec, exec, s[4:5]
	v_cmp_eq_u32_e32 vcc, v250, v149
	s_cbranch_vccz .Lp2_skip13
	s_nop 0
	v_mov_b32_e32 v246, vcc_hi
	v_mov_b32_e32 v247, vcc_lo
	v_cndmask_b32_e64 v246, v246, v247, s[48:49]
	s_and_saveexec_b64 s[4:5], vcc
	s_cbranch_execz .Lp2_join13
	v_and_b32_e32 v247, v246, v127
	v_bcnt_u32_b32 v247, v247, v119
	v_cmp_gt_u32_e32 vcc, s35, v247
	s_and_b64 exec, exec, vcc
	s_cbranch_execz .Lp2_join13
	v_cmp_gt_f32_e64 s[52:53], 0, v185
	v_not_b32_e32 v248, v185
	s_nop 0
	v_cndmask_b32_e64 v33, -|v185|, v248, s[52:53]
	v_lshl_add_u64 v[154:155], v[86:87], 0, s[0:1]
	v_lshl_add_u64 v[154:155], v[154:155], 0, v[32:33]
	v_lshl_add_u32 v248, v247, 3, v160
	ds_write_b64 v248, v[154:155] offset:2048

.Lp2_skip13:
	v_mfma_f32_32x32x16_bf16 v[16:31], v[42:45], v[230:233], v[16:31]
	v_cmp_gt_i32_e32 vcc, v197, v159
	s_and_saveexec_b64 s[4:5], s[50:51]
	s_nop 0
	v_mov_b32_e32 v246, vcc_hi
	v_mov_b32_e32 v247, vcc_lo
	v_cndmask_b32_e64 v246, v246, v247, s[48:49]
	ds_write_b32 v162, v246 offset:1048
	s_or_b64 exec, exec, s[4:5]
	v_cmp_eq_u32_e32 vcc, v197, v159
	s_cbranch_vccz .Lp2_skip14
	s_nop 0
	v_mov_b32_e32 v246, vcc_hi
	v_mov_b32_e32 v247, vcc_lo
	v_cndmask_b32_e64 v246, v246, v247, s[48:49]
	s_and_saveexec_b64 s[4:5], vcc
	s_cbranch_execz .Lp2_join14
	v_and_b32_e32 v247, v246, v127
	v_bcnt_u32_b32 v247, v247, v118
	v_cmp_gt_u32_e32 vcc, s35, v247
	s_and_b64 exec, exec, vcc
	s_cbranch_execz .Lp2_join14
	v_cmp_gt_f32_e64 s[52:53], 0, v184
	v_not_b32_e32 v248, v184
	s_nop 0
	v_cndmask_b32_e64 v33, -|v184|, v248, s[52:53]
	v_lshl_add_u64 v[154:155], v[86:87], 0, s[0:1]
	v_lshl_add_u64 v[154:155], v[154:155], 0, v[32:33]
	v_lshl_add_u32 v248, v247, 3, v161
	ds_write_b64 v248, v[154:155] offset:2048

.Lp2_skip14:
	v_mfma_f32_32x32x16_bf16 v[0:15], v[42:45], v[234:237], v[0:15]
	v_max_i32_e32 v246, 0, v222
	v_max_i32_e32 v247, 0, v214
	v_max_i32_e32 v248, 0, v223
	v_max_i32_e32 v249, 0, v215
	v_max_i32_e32 v154, 0, v224
	v_max_i32_e32 v155, 0, v216
	v_max_i32_e32 v156, 0, v225
	v_max_i32_e32 v157, 0, v217
	v_mfma_f32_32x32x16_bf16 v[16:31], v[46:49], v[238:241], v[16:31]
	v_pk_fma_f32 v[184:185], v[100:101], v[246:247], 0 op_sel_hi:[1,1,0]
	v_pk_fma_f32 v[184:185], v[102:103], v[248:249], v[184:185]
	v_pk_fma_f32 v[184:185], v[104:105], v[154:155], v[184:185]
	v_pk_fma_f32 v[184:185], v[106:107], v[156:157], v[184:185]
	v_max_i32_e32 v246, 0, v226
	v_max_i32_e32 v247, 0, v218
	v_max_i32_e32 v248, 0, v227
	v_max_i32_e32 v249, 0, v219
	v_mfma_f32_32x32x16_bf16 v[0:15], v[46:49], v[242:245], v[0:15]
	v_max_i32_e32 v154, 0, v228
	v_max_i32_e32 v155, 0, v220
	v_max_i32_e32 v156, 0, v229
	v_max_i32_e32 v157, 0, v221
	v_pk_fma_f32 v[184:185], v[108:109], v[246:247], v[184:185]
	v_pk_fma_f32 v[184:185], v[110:111], v[248:249], v[184:185]
	v_pk_fma_f32 v[184:185], v[112:113], v[154:155], v[184:185]
	v_pk_fma_f32 v[184:185], v[114:115], v[156:157], v[184:185]
	v_bfe_u32 v250, v185, 19, 12
	v_bfe_u32 v197, v184, 19, 12
	v_med3_u32 v250, v250, s94, v194
	v_med3_u32 v197, v197, s94, v194
	v_sub_u32_e32 v246, 0x86f, v250
	v_add_u32_e32 v247, 0xfffffb90, v250
	v_sub_u32_e32 v248, 0x86f, v197
	v_add_u32_e32 v249, 0xfffffb90, v197
	v_cmp_gt_f32_e32 vcc, 0, v185
	v_cmp_gt_f32_e64 s[52:53], 0, v184
	s_nop 0
	v_cndmask_b32_e32 v250, v247, v246, vcc
	v_cndmask_b32_e64 v197, v249, v248, s[52:53]
	v_cmp_gt_i32_e32 vcc, v250, v149
	s_and_saveexec_b64 s[4:5], s[50:51]
	s_nop 0
	v_mov_b32_e32 v246, vcc_hi
	v_mov_b32_e32 v247, vcc_lo
	v_cndmask_b32_e64 v246, v246, v247, s[48:49]
	ds_write_b32 v162, v246 offset:28
	s_or_b64 exec, exec, s[4:5]
	v_cmp_eq_u32_e32 vcc, v250, v149
	s_cbranch_vccz .Lp2_skip15
	s_nop 0
	v_mov_b32_e32 v246, vcc_hi
	v_mov_b32_e32 v247, vcc_lo
	v_cndmask_b32_e64 v246, v246, v247, s[48:49]
	s_and_saveexec_b64 s[4:5], vcc
	s_cbranch_execz .Lp2_join15
	v_and_b32_e32 v247, v246, v127
	v_bcnt_u32_b32 v247, v247, v119
	v_cmp_gt_u32_e32 vcc, s35, v247
	s_and_b64 exec, exec, vcc
	s_cbranch_execz .Lp2_join15
	v_cmp_gt_f32_e64 s[52:53], 0, v185
	v_not_b32_e32 v248, v185
	s_nop 0
	v_cndmask_b32_e64 v33, -|v185|, v248, s[52:53]
	v_lshl_add_u64 v[154:155], v[84:85], 0, s[0:1]
	v_lshl_add_u64 v[154:155], v[154:155], 0, v[32:33]
	v_lshl_add_u32 v248, v247, 3, v160
	ds_write_b64 v248, v[154:155] offset:2048

.Lp2_skip15:
	v_cmp_gt_i32_e32 vcc, v197, v159
	s_and_saveexec_b64 s[4:5], s[50:51]
	s_nop 0
	v_mov_b32_e32 v246, vcc_hi
	v_mov_b32_e32 v247, vcc_lo
	v_cndmask_b32_e64 v246, v246, v247, s[48:49]
	ds_write_b32 v162, v246 offset:1052
	s_or_b64 exec, exec, s[4:5]
	v_cmp_eq_u32_e32 vcc, v197, v159
	s_cbranch_vccz .Lp2_skip16
	s_nop 0
	v_mov_b32_e32 v246, vcc_hi
	v_mov_b32_e32 v247, vcc_lo
	v_cndmask_b32_e64 v246, v246, v247, s[48:49]
	s_and_saveexec_b64 s[4:5], vcc
	s_cbranch_execz .Lp2_join16
	v_and_b32_e32 v247, v246, v127
	v_bcnt_u32_b32 v247, v247, v118
	v_cmp_gt_u32_e32 vcc, s35, v247
	s_and_b64 exec, exec, vcc
	s_cbranch_execz .Lp2_join16
	v_cmp_gt_f32_e64 s[52:53], 0, v184
	v_not_b32_e32 v248, v184
	s_nop 0
	v_cndmask_b32_e64 v33, -|v184|, v248, s[52:53]
	v_lshl_add_u64 v[154:155], v[84:85], 0, s[0:1]
	v_lshl_add_u64 v[154:155], v[154:155], 0, v[32:33]
	v_lshl_add_u32 v248, v247, 3, v161
	ds_write_b64 v248, v[154:155] offset:2048

.Lp2_skip16:
	s_waitcnt lgkmcnt(0)
	s_barrier
	s_add_u32 s0, s0, 0xffffff00
	s_addc_u32 s1, s1, -1
	v_add_u32_e32 v162, 32, v162
	s_add_u32 s18, s18, 1
	s_cmp_ge_u32 s18, s13
	s_cbranch_scc1 .Lp2_drain0
	s_branch .Lp2_c1
.Lp2_drain0:
	v_max_i32_e32 v246, 0, v24
	v_max_i32_e32 v247, 0, v16
	v_max_i32_e32 v248, 0, v25
	v_max_i32_e32 v249, 0, v17
	v_max_i32_e32 v154, 0, v26
	v_max_i32_e32 v155, 0, v18
	v_max_i32_e32 v156, 0, v27
	v_max_i32_e32 v157, 0, v19
	v_pk_fma_f32 v[184:185], v[100:101], v[246:247], 0 op_sel_hi:[1,1,0]
	v_pk_fma_f32 v[184:185], v[102:103], v[248:249], v[184:185]
	v_pk_fma_f32 v[184:185], v[104:105], v[154:155], v[184:185]
	v_pk_fma_f32 v[184:185], v[106:107], v[156:157], v[184:185]
	v_max_i32_e32 v246, 0, v28
	v_max_i32_e32 v247, 0, v20
	v_max_i32_e32 v248, 0, v29
	v_max_i32_e32 v249, 0, v21
	v_max_i32_e32 v154, 0, v30
	v_max_i32_e32 v155, 0, v22
	v_max_i32_e32 v156, 0, v31
	v_max_i32_e32 v157, 0, v23
	v_pk_fma_f32 v[184:185], v[108:109], v[246:247], v[184:185]
	v_pk_fma_f32 v[184:185], v[110:111], v[248:249], v[184:185]
	v_pk_fma_f32 v[184:185], v[112:113], v[154:155], v[184:185]
	v_pk_fma_f32 v[184:185], v[114:115], v[156:157], v[184:185]
	v_bfe_u32 v250, v185, 19, 12
	v_bfe_u32 v197, v184, 19, 12
	v_med3_u32 v250, v250, s94, v194
	v_med3_u32 v197, v197, s94, v194
	v_sub_u32_e32 v246, 0x86f, v250
	v_add_u32_e32 v247, 0xfffffb90, v250
	v_sub_u32_e32 v248, 0x86f, v197
	v_add_u32_e32 v249, 0xfffffb90, v197
	v_cmp_gt_f32_e32 vcc, 0, v185
	v_cmp_gt_f32_e64 s[52:53], 0, v184
	s_nop 0
	v_cndmask_b32_e32 v250, v247, v246, vcc
	v_cndmask_b32_e64 v197, v249, v248, s[52:53]
	v_cmp_gt_i32_e32 vcc, v250, v149
	s_and_saveexec_b64 s[4:5], s[50:51]
	s_nop 0
	v_mov_b32_e32 v246, vcc_hi
	v_mov_b32_e32 v247, vcc_lo
	v_cndmask_b32_e64 v246, v246, v247, s[48:49]
	ds_write_b32 v162, v246
	s_or_b64 exec, exec, s[4:5]
	v_cmp_eq_u32_e32 vcc, v250, v149
	s_cbranch_vccz .Lp2_skip17
	s_nop 0
	v_mov_b32_e32 v246, vcc_hi
	v_mov_b32_e32 v247, vcc_lo
	v_cndmask_b32_e64 v246, v246, v247, s[48:49]
	s_and_saveexec_b64 s[4:5], vcc
	s_cbranch_execz .Lp2_join17
	v_and_b32_e32 v247, v246, v127
	v_bcnt_u32_b32 v247, v247, v119
	v_cmp_gt_u32_e32 vcc, s35, v247
	s_and_b64 exec, exec, vcc
	s_cbranch_execz .Lp2_join17
	v_cmp_gt_f32_e64 s[52:53], 0, v185
	v_not_b32_e32 v248, v185
	s_nop 0
	v_cndmask_b32_e64 v33, -|v185|, v248, s[52:53]
	v_lshl_add_u64 v[154:155], v[78:79], 0, s[0:1]
	v_lshl_add_u64 v[154:155], v[154:155], 0, v[32:33]
	v_lshl_add_u32 v248, v247, 3, v160
	ds_write_b64 v248, v[154:155] offset:2048

.Lp2_skip17:
	v_cmp_gt_i32_e32 vcc, v197, v159
	s_and_saveexec_b64 s[4:5], s[50:51]
	s_nop 0
	v_mov_b32_e32 v246, vcc_hi
	v_mov_b32_e32 v247, vcc_lo
	v_cndmask_b32_e64 v246, v246, v247, s[48:49]
	ds_write_b32 v162, v246 offset:1024
	s_or_b64 exec, exec, s[4:5]
	v_cmp_eq_u32_e32 vcc, v197, v159
	s_cbranch_vccz .Lp2_skip18
	s_nop 0
	v_mov_b32_e32 v246, vcc_hi
	v_mov_b32_e32 v247, vcc_lo
	v_cndmask_b32_e64 v246, v246, v247, s[48:49]
	s_and_saveexec_b64 s[4:5], vcc
	s_cbranch_execz .Lp2_join18
	v_and_b32_e32 v247, v246, v127
	v_bcnt_u32_b32 v247, v247, v118
	v_cmp_gt_u32_e32 vcc, s35, v247
	s_and_b64 exec, exec, vcc
	s_cbranch_execz .Lp2_join18
	v_cmp_gt_f32_e64 s[52:53], 0, v184
	v_not_b32_e32 v248, v184
	s_nop 0
	v_cndmask_b32_e64 v33, -|v184|, v248, s[52:53]
	v_lshl_add_u64 v[154:155], v[78:79], 0, s[0:1]
	v_lshl_add_u64 v[154:155], v[154:155], 0, v[32:33]
	v_lshl_add_u32 v248, v247, 3, v161
	ds_write_b64 v248, v[154:155] offset:2048

.Lp2_skip18:
	v_max_i32_e32 v246, 0, v8
	v_max_i32_e32 v247, 0, v0
	v_max_i32_e32 v248, 0, v9
	v_max_i32_e32 v249, 0, v1
	v_max_i32_e32 v154, 0, v10
	v_max_i32_e32 v155, 0, v2
	v_max_i32_e32 v156, 0, v11
	v_max_i32_e32 v157, 0, v3
	v_pk_fma_f32 v[184:185], v[100:101], v[246:247], 0 op_sel_hi:[1,1,0]
	v_pk_fma_f32 v[184:185], v[102:103], v[248:249], v[184:185]
	v_pk_fma_f32 v[184:185], v[104:105], v[154:155], v[184:185]
	v_pk_fma_f32 v[184:185], v[106:107], v[156:157], v[184:185]
	v_max_i32_e32 v246, 0, v12
	v_max_i32_e32 v247, 0, v4
	v_max_i32_e32 v248, 0, v13
	v_max_i32_e32 v249, 0, v5
	v_max_i32_e32 v154, 0, v14
	v_max_i32_e32 v155, 0, v6
	v_max_i32_e32 v156, 0, v15
	v_max_i32_e32 v157, 0, v7
	v_pk_fma_f32 v[184:185], v[108:109], v[246:247], v[184:185]
	v_pk_fma_f32 v[184:185], v[110:111], v[248:249], v[184:185]
	v_pk_fma_f32 v[184:185], v[112:113], v[154:155], v[184:185]
	v_pk_fma_f32 v[184:185], v[114:115], v[156:157], v[184:185]
	v_bfe_u32 v250, v185, 19, 12
	v_bfe_u32 v197, v184, 19, 12
	v_med3_u32 v250, v250, s94, v194
	v_med3_u32 v197, v197, s94, v194
	v_sub_u32_e32 v246, 0x86f, v250
	v_add_u32_e32 v247, 0xfffffb90, v250
	v_sub_u32_e32 v248, 0x86f, v197
	v_add_u32_e32 v249, 0xfffffb90, v197
	v_cmp_gt_f32_e32 vcc, 0, v185
	v_cmp_gt_f32_e64 s[52:53], 0, v184
	s_nop 0
	v_cndmask_b32_e32 v250, v247, v246, vcc
	v_cndmask_b32_e64 v197, v249, v248, s[52:53]
	v_cmp_gt_i32_e32 vcc, v250, v149
	s_and_saveexec_b64 s[4:5], s[50:51]
	s_nop 0
	v_mov_b32_e32 v246, vcc_hi
	v_mov_b32_e32 v247, vcc_lo
	v_cndmask_b32_e64 v246, v246, v247, s[48:49]
	ds_write_b32 v162, v246 offset:4
	s_or_b64 exec, exec, s[4:5]
	v_cmp_eq_u32_e32 vcc, v250, v149
	s_cbranch_vccz .Lp2_skip19
	s_nop 0
	v_mov_b32_e32 v246, vcc_hi
	v_mov_b32_e32 v247, vcc_lo
	v_cndmask_b32_e64 v246, v246, v247, s[48:49]
	s_and_saveexec_b64 s[4:5], vcc
	s_cbranch_execz .Lp2_join19
	v_and_b32_e32 v247, v246, v127
	v_bcnt_u32_b32 v247, v247, v119
	v_cmp_gt_u32_e32 vcc, s35, v247
	s_and_b64 exec, exec, vcc
	s_cbranch_execz .Lp2_join19
	v_cmp_gt_f32_e64 s[52:53], 0, v185
	v_not_b32_e32 v248, v185
	s_nop 0
	v_cndmask_b32_e64 v33, -|v185|, v248, s[52:53]
	v_lshl_add_u64 v[154:155], v[96:97], 0, s[0:1]
	v_lshl_add_u64 v[154:155], v[154:155], 0, v[32:33]
	v_lshl_add_u32 v248, v247, 3, v160
	ds_write_b64 v248, v[154:155] offset:2048

.Lp2_skip20:
	s_waitcnt lgkmcnt(0)
	s_barrier
	s_branch .LBB0_1140
.Lp2_drain1:
	v_max_i32_e32 v246, 0, v206
	v_max_i32_e32 v247, 0, v198
	v_max_i32_e32 v248, 0, v207
	v_max_i32_e32 v249, 0, v199
	v_max_i32_e32 v154, 0, v208
	v_max_i32_e32 v155, 0, v200
	v_max_i32_e32 v156, 0, v209
	v_max_i32_e32 v157, 0, v201
	v_pk_fma_f32 v[184:185], v[100:101], v[246:247], 0 op_sel_hi:[1,1,0]
	v_pk_fma_f32 v[184:185], v[102:103], v[248:249], v[184:185]
	v_pk_fma_f32 v[184:185], v[104:105], v[154:155], v[184:185]
	v_pk_fma_f32 v[184:185], v[106:107], v[156:157], v[184:185]
	v_max_i32_e32 v246, 0, v210
	v_max_i32_e32 v247, 0, v202
	v_max_i32_e32 v248, 0, v211
	v_max_i32_e32 v249, 0, v203
	v_max_i32_e32 v154, 0, v212
	v_max_i32_e32 v155, 0, v204
	v_max_i32_e32 v156, 0, v213
	v_max_i32_e32 v157, 0, v205
	v_pk_fma_f32 v[184:185], v[108:109], v[246:247], v[184:185]
	v_pk_fma_f32 v[184:185], v[110:111], v[248:249], v[184:185]
	v_pk_fma_f32 v[184:185], v[112:113], v[154:155], v[184:185]
	v_pk_fma_f32 v[184:185], v[114:115], v[156:157], v[184:185]
	v_bfe_u32 v250, v185, 19, 12
	v_bfe_u32 v197, v184, 19, 12
	v_med3_u32 v250, v250, s94, v194
	v_med3_u32 v197, v197, s94, v194
	v_sub_u32_e32 v246, 0x86f, v250
	v_add_u32_e32 v247, 0xfffffb90, v250
	v_sub_u32_e32 v248, 0x86f, v197
	v_add_u32_e32 v249, 0xfffffb90, v197
	v_cmp_gt_f32_e32 vcc, 0, v185
	v_cmp_gt_f32_e64 s[52:53], 0, v184
	s_nop 0
	v_cndmask_b32_e32 v250, v247, v246, vcc
	v_cndmask_b32_e64 v197, v249, v248, s[52:53]
	v_cmp_gt_i32_e32 vcc, v250, v149
	s_and_saveexec_b64 s[4:5], s[50:51]
	s_nop 0
	v_mov_b32_e32 v246, vcc_hi
	v_mov_b32_e32 v247, vcc_lo
	v_cndmask_b32_e64 v246, v246, v247, s[48:49]
	ds_write_b32 v162, v246 offset:8
	s_or_b64 exec, exec, s[4:5]
	v_cmp_eq_u32_e32 vcc, v250, v149
	s_cbranch_vccz .Lp2_skip21
	s_nop 0
	v_mov_b32_e32 v246, vcc_hi
	v_mov_b32_e32 v247, vcc_lo
	v_cndmask_b32_e64 v246, v246, v247, s[48:49]
	s_and_saveexec_b64 s[4:5], vcc
	s_cbranch_execz .Lp2_join21
	v_and_b32_e32 v247, v246, v127
	v_bcnt_u32_b32 v247, v247, v119
	v_cmp_gt_u32_e32 vcc, s35, v247
	s_and_b64 exec, exec, vcc
	s_cbranch_execz .Lp2_join21
	v_cmp_gt_f32_e64 s[52:53], 0, v185
	v_not_b32_e32 v248, v185
	s_nop 0
	v_cndmask_b32_e64 v33, -|v185|, v248, s[52:53]
	v_lshl_add_u64 v[154:155], v[92:93], 0, s[0:1]
	v_lshl_add_u64 v[154:155], v[154:155], 0, v[32:33]
	v_lshl_add_u32 v248, v247, 3, v160
	ds_write_b64 v248, v[154:155] offset:2048

.Lp2_skip21:
	v_cmp_gt_i32_e32 vcc, v197, v159
	s_and_saveexec_b64 s[4:5], s[50:51]
	s_nop 0
	v_mov_b32_e32 v246, vcc_hi
	v_mov_b32_e32 v247, vcc_lo
	v_cndmask_b32_e64 v246, v246, v247, s[48:49]
	ds_write_b32 v162, v246 offset:1032
	s_or_b64 exec, exec, s[4:5]
	v_cmp_eq_u32_e32 vcc, v197, v159
	s_cbranch_vccz .Lp2_skip22
	s_nop 0
	v_mov_b32_e32 v246, vcc_hi
	v_mov_b32_e32 v247, vcc_lo
	v_cndmask_b32_e64 v246, v246, v247, s[48:49]
	s_and_saveexec_b64 s[4:5], vcc
	s_cbranch_execz .Lp2_join22
	v_and_b32_e32 v247, v246, v127
	v_bcnt_u32_b32 v247, v247, v118
	v_cmp_gt_u32_e32 vcc, s35, v247
	s_and_b64 exec, exec, vcc
	s_cbranch_execz .Lp2_join22
	v_cmp_gt_f32_e64 s[52:53], 0, v184
	v_not_b32_e32 v248, v184
	s_nop 0
	v_cndmask_b32_e64 v33, -|v184|, v248, s[52:53]
	v_lshl_add_u64 v[154:155], v[92:93], 0, s[0:1]
	v_lshl_add_u64 v[154:155], v[154:155], 0, v[32:33]
	v_lshl_add_u32 v248, v247, 3, v161
	ds_write_b64 v248, v[154:155] offset:2048

.Lp2_skip22:
	v_max_i32_e32 v246, 0, v222
	v_max_i32_e32 v247, 0, v214
	v_max_i32_e32 v248, 0, v223
	v_max_i32_e32 v249, 0, v215
	v_max_i32_e32 v154, 0, v224
	v_max_i32_e32 v155, 0, v216
	v_max_i32_e32 v156, 0, v225
	v_max_i32_e32 v157, 0, v217
	v_pk_fma_f32 v[184:185], v[100:101], v[246:247], 0 op_sel_hi:[1,1,0]
	v_pk_fma_f32 v[184:185], v[102:103], v[248:249], v[184:185]
	v_pk_fma_f32 v[184:185], v[104:105], v[154:155], v[184:185]
	v_pk_fma_f32 v[184:185], v[106:107], v[156:157], v[184:185]
	v_max_i32_e32 v246, 0, v226
	v_max_i32_e32 v247, 0, v218
	v_max_i32_e32 v248, 0, v227
	v_max_i32_e32 v249, 0, v219
	v_max_i32_e32 v154, 0, v228
	v_max_i32_e32 v155, 0, v220
	v_max_i32_e32 v156, 0, v229
	v_max_i32_e32 v157, 0, v221
	v_pk_fma_f32 v[184:185], v[108:109], v[246:247], v[184:185]
	v_pk_fma_f32 v[184:185], v[110:111], v[248:249], v[184:185]
	v_pk_fma_f32 v[184:185], v[112:113], v[154:155], v[184:185]
	v_pk_fma_f32 v[184:185], v[114:115], v[156:157], v[184:185]
	v_bfe_u32 v250, v185, 19, 12
	v_bfe_u32 v197, v184, 19, 12
	v_med3_u32 v250, v250, s94, v194
	v_med3_u32 v197, v197, s94, v194
	v_sub_u32_e32 v246, 0x86f, v250
	v_add_u32_e32 v247, 0xfffffb90, v250
	v_sub_u32_e32 v248, 0x86f, v197
	v_add_u32_e32 v249, 0xfffffb90, v197
	v_cmp_gt_f32_e32 vcc, 0, v185
	v_cmp_gt_f32_e64 s[52:53], 0, v184
	s_nop 0
	v_cndmask_b32_e32 v250, v247, v246, vcc
	v_cndmask_b32_e64 v197, v249, v248, s[52:53]
	v_cmp_gt_i32_e32 vcc, v250, v149
	s_and_saveexec_b64 s[4:5], s[50:51]
	s_nop 0
	v_mov_b32_e32 v246, vcc_hi
	v_mov_b32_e32 v247, vcc_lo
	v_cndmask_b32_e64 v246, v246, v247, s[48:49]
	ds_write_b32 v162, v246 offset:12
	s_or_b64 exec, exec, s[4:5]
	v_cmp_eq_u32_e32 vcc, v250, v149
	s_cbranch_vccz .Lp2_skip23
	s_nop 0
	v_mov_b32_e32 v246, vcc_hi
	v_mov_b32_e32 v247, vcc_lo
	v_cndmask_b32_e64 v246, v246, v247, s[48:49]
	s_and_saveexec_b64 s[4:5], vcc
	s_cbranch_execz .Lp2_join23
	v_and_b32_e32 v247, v246, v127
	v_bcnt_u32_b32 v247, v247, v119
	v_cmp_gt_u32_e32 vcc, s35, v247
	s_and_b64 exec, exec, vcc
	s_cbranch_execz .Lp2_join23
	v_cmp_gt_f32_e64 s[52:53], 0, v185
	v_not_b32_e32 v248, v185
	s_nop 0
	v_cndmask_b32_e64 v33, -|v185|, v248, s[52:53]
	v_lshl_add_u64 v[154:155], v[94:95], 0, s[0:1]
	v_lshl_add_u64 v[154:155], v[154:155], 0, v[32:33]
	v_lshl_add_u32 v248, v247, 3, v160
	ds_write_b64 v248, v[154:155] offset:2048

.Lp2_drain2:
	v_max_i32_e32 v246, 0, v24
	v_max_i32_e32 v247, 0, v16
	v_max_i32_e32 v248, 0, v25
	v_max_i32_e32 v249, 0, v17
	v_max_i32_e32 v154, 0, v26
	v_max_i32_e32 v155, 0, v18
	v_max_i32_e32 v156, 0, v27
	v_max_i32_e32 v157, 0, v19
	v_pk_fma_f32 v[184:185], v[100:101], v[246:247], 0 op_sel_hi:[1,1,0]
	v_pk_fma_f32 v[184:185], v[102:103], v[248:249], v[184:185]
	v_pk_fma_f32 v[184:185], v[104:105], v[154:155], v[184:185]
	v_pk_fma_f32 v[184:185], v[106:107], v[156:157], v[184:185]
	v_max_i32_e32 v246, 0, v28
	v_max_i32_e32 v247, 0, v20
	v_max_i32_e32 v248, 0, v29
	v_max_i32_e32 v249, 0, v21
	v_max_i32_e32 v154, 0, v30
	v_max_i32_e32 v155, 0, v22
	v_max_i32_e32 v156, 0, v31
	v_max_i32_e32 v157, 0, v23
	v_pk_fma_f32 v[184:185], v[108:109], v[246:247], v[184:185]
	v_pk_fma_f32 v[184:185], v[110:111], v[248:249], v[184:185]
	v_pk_fma_f32 v[184:185], v[112:113], v[154:155], v[184:185]
	v_pk_fma_f32 v[184:185], v[114:115], v[156:157], v[184:185]
	v_bfe_u32 v250, v185, 19, 12
	v_bfe_u32 v197, v184, 19, 12
	v_med3_u32 v250, v250, s94, v194
	v_med3_u32 v197, v197, s94, v194
	v_sub_u32_e32 v246, 0x86f, v250
	v_add_u32_e32 v247, 0xfffffb90, v250
	v_sub_u32_e32 v248, 0x86f, v197
	v_add_u32_e32 v249, 0xfffffb90, v197
	v_cmp_gt_f32_e32 vcc, 0, v185
	v_cmp_gt_f32_e64 s[52:53], 0, v184
	s_nop 0
	v_cndmask_b32_e32 v250, v247, v246, vcc
	v_cndmask_b32_e64 v197, v249, v248, s[52:53]
	v_cmp_gt_i32_e32 vcc, v250, v149
	s_and_saveexec_b64 s[4:5], s[50:51]
	s_nop 0
	v_mov_b32_e32 v246, vcc_hi
	v_mov_b32_e32 v247, vcc_lo
	v_cndmask_b32_e64 v246, v246, v247, s[48:49]
	ds_write_b32 v162, v246 offset:16
	s_or_b64 exec, exec, s[4:5]
	v_cmp_eq_u32_e32 vcc, v250, v149
	s_cbranch_vccz .Lp2_skip25
	s_nop 0
	v_mov_b32_e32 v246, vcc_hi
	v_mov_b32_e32 v247, vcc_lo
	v_cndmask_b32_e64 v246, v246, v247, s[48:49]
	s_and_saveexec_b64 s[4:5], vcc
	s_cbranch_execz .Lp2_join25
	v_and_b32_e32 v247, v246, v127
	v_bcnt_u32_b32 v247, v247, v119
	v_cmp_gt_u32_e32 vcc, s35, v247
	s_and_b64 exec, exec, vcc
	s_cbranch_execz .Lp2_join25
	v_cmp_gt_f32_e64 s[52:53], 0, v185
	v_not_b32_e32 v248, v185
	s_nop 0
	v_cndmask_b32_e64 v33, -|v185|, v248, s[52:53]
	v_lshl_add_u64 v[154:155], v[90:91], 0, s[0:1]
	v_lshl_add_u64 v[154:155], v[154:155], 0, v[32:33]
	v_lshl_add_u32 v248, v247, 3, v160
	ds_write_b64 v248, v[154:155] offset:2048

.Lp2_skip25:
	v_cmp_gt_i32_e32 vcc, v197, v159
	s_and_saveexec_b64 s[4:5], s[50:51]
	s_nop 0
	v_mov_b32_e32 v246, vcc_hi
	v_mov_b32_e32 v247, vcc_lo
	v_cndmask_b32_e64 v246, v246, v247, s[48:49]
	ds_write_b32 v162, v246 offset:1040
	s_or_b64 exec, exec, s[4:5]
	v_cmp_eq_u32_e32 vcc, v197, v159
	s_cbranch_vccz .Lp2_skip26
	s_nop 0
	v_mov_b32_e32 v246, vcc_hi
	v_mov_b32_e32 v247, vcc_lo
	v_cndmask_b32_e64 v246, v246, v247, s[48:49]
	s_and_saveexec_b64 s[4:5], vcc
	s_cbranch_execz .Lp2_join26
	v_and_b32_e32 v247, v246, v127
	v_bcnt_u32_b32 v247, v247, v118
	v_cmp_gt_u32_e32 vcc, s35, v247
	s_and_b64 exec, exec, vcc
	s_cbranch_execz .Lp2_join26
	v_cmp_gt_f32_e64 s[52:53], 0, v184
	v_not_b32_e32 v248, v184
	s_nop 0
	v_cndmask_b32_e64 v33, -|v184|, v248, s[52:53]
	v_lshl_add_u64 v[154:155], v[90:91], 0, s[0:1]
	v_lshl_add_u64 v[154:155], v[154:155], 0, v[32:33]
	v_lshl_add_u32 v248, v247, 3, v161
	ds_write_b64 v248, v[154:155] offset:2048

.Lp2_skip26:
	v_max_i32_e32 v246, 0, v8
	v_max_i32_e32 v247, 0, v0
	v_max_i32_e32 v248, 0, v9
	v_max_i32_e32 v249, 0, v1
	v_max_i32_e32 v154, 0, v10
	v_max_i32_e32 v155, 0, v2
	v_max_i32_e32 v156, 0, v11
	v_max_i32_e32 v157, 0, v3
	v_pk_fma_f32 v[184:185], v[100:101], v[246:247], 0 op_sel_hi:[1,1,0]
	v_pk_fma_f32 v[184:185], v[102:103], v[248:249], v[184:185]
	v_pk_fma_f32 v[184:185], v[104:105], v[154:155], v[184:185]
	v_pk_fma_f32 v[184:185], v[106:107], v[156:157], v[184:185]
	v_max_i32_e32 v246, 0, v12
	v_max_i32_e32 v247, 0, v4
	v_max_i32_e32 v248, 0, v13
	v_max_i32_e32 v249, 0, v5
	v_max_i32_e32 v154, 0, v14
	v_max_i32_e32 v155, 0, v6
	v_max_i32_e32 v156, 0, v15
	v_max_i32_e32 v157, 0, v7
	v_pk_fma_f32 v[184:185], v[108:109], v[246:247], v[184:185]
	v_pk_fma_f32 v[184:185], v[110:111], v[248:249], v[184:185]
	v_pk_fma_f32 v[184:185], v[112:113], v[154:155], v[184:185]
	v_pk_fma_f32 v[184:185], v[114:115], v[156:157], v[184:185]
	v_bfe_u32 v250, v185, 19, 12
	v_bfe_u32 v197, v184, 19, 12
	v_med3_u32 v250, v250, s94, v194
	v_med3_u32 v197, v197, s94, v194
	v_sub_u32_e32 v246, 0x86f, v250
	v_add_u32_e32 v247, 0xfffffb90, v250
	v_sub_u32_e32 v248, 0x86f, v197
	v_add_u32_e32 v249, 0xfffffb90, v197
	v_cmp_gt_f32_e32 vcc, 0, v185
	v_cmp_gt_f32_e64 s[52:53], 0, v184
	s_nop 0
	v_cndmask_b32_e32 v250, v247, v246, vcc
	v_cndmask_b32_e64 v197, v249, v248, s[52:53]
	v_cmp_gt_i32_e32 vcc, v250, v149
	s_and_saveexec_b64 s[4:5], s[50:51]
	s_nop 0
	v_mov_b32_e32 v246, vcc_hi
	v_mov_b32_e32 v247, vcc_lo
	v_cndmask_b32_e64 v246, v246, v247, s[48:49]
	ds_write_b32 v162, v246 offset:20
	s_or_b64 exec, exec, s[4:5]
	v_cmp_eq_u32_e32 vcc, v250, v149
	s_cbranch_vccz .Lp2_skip27
	s_nop 0
	v_mov_b32_e32 v246, vcc_hi
	v_mov_b32_e32 v247, vcc_lo
	v_cndmask_b32_e64 v246, v246, v247, s[48:49]
	s_and_saveexec_b64 s[4:5], vcc
	s_cbranch_execz .Lp2_join27
	v_and_b32_e32 v247, v246, v127
	v_bcnt_u32_b32 v247, v247, v119
	v_cmp_gt_u32_e32 vcc, s35, v247
	s_and_b64 exec, exec, vcc
	s_cbranch_execz .Lp2_join27
	v_cmp_gt_f32_e64 s[52:53], 0, v185
	v_not_b32_e32 v248, v185
	s_nop 0
	v_cndmask_b32_e64 v33, -|v185|, v248, s[52:53]
	v_lshl_add_u64 v[154:155], v[88:89], 0, s[0:1]
	v_lshl_add_u64 v[154:155], v[154:155], 0, v[32:33]
	v_lshl_add_u32 v248, v247, 3, v160
	ds_write_b64 v248, v[154:155] offset:2048

.Lp2_drain3:
	v_max_i32_e32 v246, 0, v206
	v_max_i32_e32 v247, 0, v198
	v_max_i32_e32 v248, 0, v207
	v_max_i32_e32 v249, 0, v199
	v_max_i32_e32 v154, 0, v208
	v_max_i32_e32 v155, 0, v200
	v_max_i32_e32 v156, 0, v209
	v_max_i32_e32 v157, 0, v201
	v_pk_fma_f32 v[184:185], v[100:101], v[246:247], 0 op_sel_hi:[1,1,0]
	v_pk_fma_f32 v[184:185], v[102:103], v[248:249], v[184:185]
	v_pk_fma_f32 v[184:185], v[104:105], v[154:155], v[184:185]
	v_pk_fma_f32 v[184:185], v[106:107], v[156:157], v[184:185]
	v_max_i32_e32 v246, 0, v210
	v_max_i32_e32 v247, 0, v202
	v_max_i32_e32 v248, 0, v211
	v_max_i32_e32 v249, 0, v203
	v_max_i32_e32 v154, 0, v212
	v_max_i32_e32 v155, 0, v204
	v_max_i32_e32 v156, 0, v213
	v_max_i32_e32 v157, 0, v205
	v_pk_fma_f32 v[184:185], v[108:109], v[246:247], v[184:185]
	v_pk_fma_f32 v[184:185], v[110:111], v[248:249], v[184:185]
	v_pk_fma_f32 v[184:185], v[112:113], v[154:155], v[184:185]
	v_pk_fma_f32 v[184:185], v[114:115], v[156:157], v[184:185]
	v_bfe_u32 v250, v185, 19, 12
	v_bfe_u32 v197, v184, 19, 12
	v_med3_u32 v250, v250, s94, v194
	v_med3_u32 v197, v197, s94, v194
	v_sub_u32_e32 v246, 0x86f, v250
	v_add_u32_e32 v247, 0xfffffb90, v250
	v_sub_u32_e32 v248, 0x86f, v197
	v_add_u32_e32 v249, 0xfffffb90, v197
	v_cmp_gt_f32_e32 vcc, 0, v185
	v_cmp_gt_f32_e64 s[52:53], 0, v184
	s_nop 0
	v_cndmask_b32_e32 v250, v247, v246, vcc
	v_cndmask_b32_e64 v197, v249, v248, s[52:53]
	v_cmp_gt_i32_e32 vcc, v250, v149
	s_and_saveexec_b64 s[4:5], s[50:51]
	s_nop 0
	v_mov_b32_e32 v246, vcc_hi
	v_mov_b32_e32 v247, vcc_lo
	v_cndmask_b32_e64 v246, v246, v247, s[48:49]
	ds_write_b32 v162, v246 offset:24
	s_or_b64 exec, exec, s[4:5]
	v_cmp_eq_u32_e32 vcc, v250, v149
	s_cbranch_vccz .Lp2_skip29
	s_nop 0
	v_mov_b32_e32 v246, vcc_hi
	v_mov_b32_e32 v247, vcc_lo
	v_cndmask_b32_e64 v246, v246, v247, s[48:49]
	s_and_saveexec_b64 s[4:5], vcc
	s_cbranch_execz .Lp2_join29
	v_and_b32_e32 v247, v246, v127
	v_bcnt_u32_b32 v247, v247, v119
	v_cmp_gt_u32_e32 vcc, s35, v247
	s_and_b64 exec, exec, vcc
	s_cbranch_execz .Lp2_join29
	v_cmp_gt_f32_e64 s[52:53], 0, v185
	v_not_b32_e32 v248, v185
	s_nop 0
	v_cndmask_b32_e64 v33, -|v185|, v248, s[52:53]
	v_lshl_add_u64 v[154:155], v[86:87], 0, s[0:1]
	v_lshl_add_u64 v[154:155], v[154:155], 0, v[32:33]
	v_lshl_add_u32 v248, v247, 3, v160
	ds_write_b64 v248, v[154:155] offset:2048

.Lp2_skip29:
	v_cmp_gt_i32_e32 vcc, v197, v159
	s_and_saveexec_b64 s[4:5], s[50:51]
	s_nop 0
	v_mov_b32_e32 v246, vcc_hi
	v_mov_b32_e32 v247, vcc_lo
	v_cndmask_b32_e64 v246, v246, v247, s[48:49]
	ds_write_b32 v162, v246 offset:1048
	s_or_b64 exec, exec, s[4:5]
	v_cmp_eq_u32_e32 vcc, v197, v159
	s_cbranch_vccz .Lp2_skip30
	s_nop 0
	v_mov_b32_e32 v246, vcc_hi
	v_mov_b32_e32 v247, vcc_lo
	v_cndmask_b32_e64 v246, v246, v247, s[48:49]
	s_and_saveexec_b64 s[4:5], vcc
	s_cbranch_execz .Lp2_join30
	v_and_b32_e32 v247, v246, v127
	v_bcnt_u32_b32 v247, v247, v118
	v_cmp_gt_u32_e32 vcc, s35, v247
	s_and_b64 exec, exec, vcc
	s_cbranch_execz .Lp2_join30
	v_cmp_gt_f32_e64 s[52:53], 0, v184
	v_not_b32_e32 v248, v184
	s_nop 0
	v_cndmask_b32_e64 v33, -|v184|, v248, s[52:53]
	v_lshl_add_u64 v[154:155], v[86:87], 0, s[0:1]
	v_lshl_add_u64 v[154:155], v[154:155], 0, v[32:33]
	v_lshl_add_u32 v248, v247, 3, v161
	ds_write_b64 v248, v[154:155] offset:2048

.Lp2_skip30:
	v_max_i32_e32 v246, 0, v222
	v_max_i32_e32 v247, 0, v214
	v_max_i32_e32 v248, 0, v223
	v_max_i32_e32 v249, 0, v215
	v_max_i32_e32 v154, 0, v224
	v_max_i32_e32 v155, 0, v216
	v_max_i32_e32 v156, 0, v225
	v_max_i32_e32 v157, 0, v217
	v_pk_fma_f32 v[184:185], v[100:101], v[246:247], 0 op_sel_hi:[1,1,0]
	v_pk_fma_f32 v[184:185], v[102:103], v[248:249], v[184:185]
	v_pk_fma_f32 v[184:185], v[104:105], v[154:155], v[184:185]
	v_pk_fma_f32 v[184:185], v[106:107], v[156:157], v[184:185]
	v_max_i32_e32 v246, 0, v226
	v_max_i32_e32 v247, 0, v218
	v_max_i32_e32 v248, 0, v227
	v_max_i32_e32 v249, 0, v219
	v_max_i32_e32 v154, 0, v228
	v_max_i32_e32 v155, 0, v220
	v_max_i32_e32 v156, 0, v229
	v_max_i32_e32 v157, 0, v221
	v_pk_fma_f32 v[184:185], v[108:109], v[246:247], v[184:185]
	v_pk_fma_f32 v[184:185], v[110:111], v[248:249], v[184:185]
	v_pk_fma_f32 v[184:185], v[112:113], v[154:155], v[184:185]
	v_pk_fma_f32 v[184:185], v[114:115], v[156:157], v[184:185]
	v_bfe_u32 v250, v185, 19, 12
	v_bfe_u32 v197, v184, 19, 12
	v_med3_u32 v250, v250, s94, v194
	v_med3_u32 v197, v197, s94, v194
	v_sub_u32_e32 v246, 0x86f, v250
	v_add_u32_e32 v247, 0xfffffb90, v250
	v_sub_u32_e32 v248, 0x86f, v197
	v_add_u32_e32 v249, 0xfffffb90, v197
	v_cmp_gt_f32_e32 vcc, 0, v185
	v_cmp_gt_f32_e64 s[52:53], 0, v184
	s_nop 0
	v_cndmask_b32_e32 v250, v247, v246, vcc
	v_cndmask_b32_e64 v197, v249, v248, s[52:53]
	v_cmp_gt_i32_e32 vcc, v250, v149
	s_and_saveexec_b64 s[4:5], s[50:51]
	s_nop 0
	v_mov_b32_e32 v246, vcc_hi
	v_mov_b32_e32 v247, vcc_lo
	v_cndmask_b32_e64 v246, v246, v247, s[48:49]
	ds_write_b32 v162, v246 offset:28
	s_or_b64 exec, exec, s[4:5]
	v_cmp_eq_u32_e32 vcc, v250, v149
	s_cbranch_vccz .Lp2_skip31
	s_nop 0
	v_mov_b32_e32 v246, vcc_hi
	v_mov_b32_e32 v247, vcc_lo
	v_cndmask_b32_e64 v246, v246, v247, s[48:49]
	s_and_saveexec_b64 s[4:5], vcc
	s_cbranch_execz .Lp2_join31
	v_and_b32_e32 v247, v246, v127
	v_bcnt_u32_b32 v247, v247, v119
	v_cmp_gt_u32_e32 vcc, s35, v247
	s_and_b64 exec, exec, vcc
	s_cbranch_execz .Lp2_join31
	v_cmp_gt_f32_e64 s[52:53], 0, v185
	v_not_b32_e32 v248, v185
	s_nop 0
	v_cndmask_b32_e64 v33, -|v185|, v248, s[52:53]
	v_lshl_add_u64 v[154:155], v[84:85], 0, s[0:1]
	v_lshl_add_u64 v[154:155], v[154:155], 0, v[32:33]
	v_lshl_add_u32 v248, v247, 3, v160
	ds_write_b64 v248, v[154:155] offset:2048
